# attention V phase: the three 64-bit v_lshl_add_u64 DMA-address increments replaced by v_add_co/v_addc pairs with literal strides (instruction selection)
# speedup vs baseline: 1.0029x; 1.0004x over previous
; #define SBAR() __builtin_amdgcn_sched_barrier(0)
; #define DMA_K(t, slot) do { if constexpr ((VAR & 16) != 0) break; __builtin_amdgcn_global_load_lds((const unsigned*)(ksrc + (size_t)TT(t) * 64 * KVW), (LAS unsigned*)(kdst + (slot) * KSLOT), 16, 0, 0); \
;                             __builtin_amdgcn_global_load_lds((const unsigned*)(rsrc + (size_t)TT(t) * 64 * ROPE), (LAS unsigned*)(rdst + (slot) * KSLOT), 16, 0, 0); } while (0)
; #define DMA_V(t, slot) do { if constexpr ((VAR & 16) == 0) __builtin_amdgcn_global_load_lds((const unsigned*)(vsrc + (size_t)TT(t) * 64 * KVW), (LAS unsigned*)(vdst + (slot) * VSLOT), 16, 0, 0); } while (0)
; #define KLOAD(slot) do { const LAS unsigned char* kb_ = kb0 + (slot) * KSLOT; _Pragma("unroll") for (int d0 = 0; d0 < 6; ++d0) { kf[2 * d0] = *(const LAS bf16x8*)(kb_ + d0 * 512); kf[2 * d0 + 1] = *(const LAS bf16x8*)(kb_ + d0 * 512 + 6144); } } while (0)
; #define RESC(al) do { if (__any((al) < 1.f)) { if (hi == 0) al_l[r32] = (al); asm volatile("s_waitcnt lgkmcnt(0)" ::: "memory"); \
;         _Pragma("unroll") for (int d_ = 0; d_ < 2; ++d_) _Pragma("unroll") for (int r = 0; r < 16; ++r) o[d_][r] *= al_l[crow(r, hi)]; } } while (0)
; #define MASKT(P0_, P1_, t) do { const int kbm_ = TT(t) * 64; if (kbm_ + 63 > qlo) mask_tile(P0_, P1_, qm - kbm_); } while (0)
; #define PBAR_M(t) do { if ((t) + 3 < NT) { WAIT_BAR(6); } else { WAIT_BAR(0); } } while (0)
; template <int VAR> __device__ __forceinline__ void block(const bf16* Q, const bf16* KVB, const bf16* KR, const float* cosT, bf16* OB, LAS unsigned char* lds, int b, int h, int qb, int t0, int wv, ...
;     ...
;     for (int t = 1; t < NT; ++t) {
;         PBAR_M(t);
;         { if (t + 3 < NT) DMA_K(t + 3, (sk + 3) & 3); if (t + 2 < NT) DMA_V(t + 2, (sk + 2) & 3); }
;         SBAR();
;         KLOAD(sk); VREAD(sv);
;         SBAR();
;         QK(px0, px1);
;         SBAR(); asm volatile("s_waitcnt lgkmcnt(0)" ::: "memory"); SBAR();
;         PVALL();
;         PBAR_V(t);
;         MASKT(px0, px1, t);
;         float pm_, alX = 1.f; ROWMAX(px0, px1, pm_);
;         if (__builtin_expect(__any(pm_ > THR), 0)) { const float dl_ = fmaxf(pm_, 0.f); SHIFT(px0, px1, dl_); alX = __builtin_amdgcn_exp2f(-dl_); }
;         TILE_VALU(alX);
;         pa0 = pn0; pa1 = pn1; pa2 = pn2; pa3 = pn3;
;         RESC(alX);
;         sk = (sk + 1) & 3; sv = (sv + 1) & 3;
.LBB0_1422:
	s_add_i32 s4, s82, 1
	s_and_b32 s82, s4, 3
	s_add_i32 s4, s68, 1
	s_add_i32 s85, s85, 1
	s_and_b32 s68, s4, 3
	s_add_i32 s4, s67, s85
	s_add_i32 s33, s33, 64
	v_subrev_u32_e32 v173, 64, v173
	v_add_co_u32_e32 v154, vcc, 0x40000, v154
	v_addc_co_u32_e32 v155, vcc, 0, v155, vcc
	v_add_co_u32_e32 v156, vcc, 0x1000, v156
	v_addc_co_u32_e32 v157, vcc, 0, v157, vcc
	v_add_co_u32_e32 v158, vcc, 0x40000, v158
	v_addc_co_u32_e32 v159, vcc, 0, v159, vcc
	v_cvt_pk_bf16_f32 v142, v194, v195
	v_cvt_pk_bf16_f32 v143, v196, v197
	v_cvt_pk_bf16_f32 v136, v198, v199
	v_cvt_pk_bf16_f32 v137, v200, v201
	v_cvt_pk_bf16_f32 v138, v202, v203
	v_cvt_pk_bf16_f32 v139, v204, v205
	v_cvt_pk_bf16_f32 v132, v174, v175
	v_cvt_pk_bf16_f32 v133, v176, v177
	v_cvt_pk_bf16_f32 v134, v178, v179
	v_cvt_pk_bf16_f32 v135, v180, v181
	v_cvt_pk_bf16_f32 v128, v182, v183
	v_cvt_pk_bf16_f32 v129, v184, v185
	v_cvt_pk_bf16_f32 v130, v186, v187
	v_cvt_pk_bf16_f32 v131, v188, v189
	s_cmp_eq_u32 s4, 4
	s_cbranch_scc1 .LBB0_1430
	s_cmp_ge_u32 s85, s66
	s_cselect_b64 s[4:5], -1, 0
	s_cbranch_scc1 .Lat_mbar0
	s_waitcnt vmcnt(6) lgkmcnt(0)
	s_barrier
	s_branch .Lat_mreads
